# static s_setprio 1 for the GLA scan producer waves (the critical path of each scan step) for the duration of their item loop
# speedup vs baseline: 1.0014x; 1.0014x over previous
; #define G2_BAR() do { asm volatile("s_waitcnt lgkmcnt(0)" ::: "memory"); __builtin_amdgcn_s_barrier(); asm volatile("" ::: "memory"); } while (0)
; __device__ __forceinline__ void gla_scan_phase2(LAS unsigned char* lds, const bf16_t* proj, const float* gbuf, const float* wgu  , const float* bg  ,
;                                                 bf16_t* ob0, bf16_t* ob1) {
;     ...
;                     G2_BAR();
;                 } else { G2_BAR(); G2_BAR(); G2_BAR(); G2_BAR(); }
.LBB0_211:
	s_setprio 0
	s_waitcnt lgkmcnt(0)
	s_barrier
	s_waitcnt lgkmcnt(0)
	s_barrier
	s_waitcnt lgkmcnt(0)
	s_barrier
	s_waitcnt lgkmcnt(0)
	s_barrier
	v_readlane_b32 s80, v251, 11
	v_readlane_b32 s81, v251, 12
	s_movk_i32 s83, 0x800

; __device__ __forceinline__ unsigned pk2(float lo, float hi) { f32x2 v = {lo, hi}; bf16x2_t b = __builtin_convertvector(v, bf16x2_t); return __builtin_bit_cast(unsigned, b); }
; __device__ __forceinline__ float bflo(unsigned w) { return __uint_as_float(w << 16); }
; __device__ __forceinline__ void gla_scan_phase2(LAS unsigned char* lds, const bf16_t* proj, const float* gbuf, const float* wgu  , const float* bg  ,
;                                                 bf16_t* ob0, bf16_t* ob1) {
;     ...
;         if (wave < 4) {
;             const int d = tid & 127, seg = (tid >> 7) & 1;
;             const int zd = wave;
;             bf16x8 wbh, wbl;
;             {
;                 unsigned hi_[4], lo_[4];
; #pragma unroll
;                 for (int q = 0; q < 4; ++q) {
;                     const float w0 = wgu[(size_t)(dir * 16 + 8 * hh + 2 * q) * 512 + h * 128 + 32 * zd + r], w1 = wgu[(size_t)(dir * 16 + 8 * hh + 2 * q + 1) * 512 + h * 128 + 32 * zd + r];
;                     hi_[q] = pk2(w0, w1); lo_[q] = pk2(w0 - bflo(hi_[q]), w1 - bfhi(hi_[q]));
;                 }
;                 wbh = __builtin_bit_cast(bf16x8, (u32x4){hi_[0], hi_[1], hi_[2], hi_[3]}); wbl = __builtin_bit_cast(bf16x8, (u32x4){lo_[0], lo_[1], lo_[2], lo_[3]});
;             }
;             const float zbias = bg[dir * 512 + h * 128 + 32 * zd + r];
;             const __amdgpu_buffer_rsrc_t prs = __builtin_amdgcn_make_buffer_rsrc((void*)proj, 0, (unsigned)((size_t)MTOK * GINP * 2), 0x00020000);
;             const unsigned qvoff = (unsigned)((16 * seg * GINP + h * 128 + d) * 2), vvoff = (unsigned)((16 * seg * GINP + 1024 + h * 256 + 2 * d) * 2);
;             f32x4 gna, gnb;
;             { const float* grow = gbuf + (size_t)(b * SEQ + (dir ? NCH - 1 : 0) * CH + r) * 32 + dir * 16 + 8 * hh; gna = *(const f32x4*)grow; gnb = *(const f32x4*)(grow + 4); }
;     ...
;                     for (int ii = 0; ii < 16; ++ii) { qv[ii] = __builtin_amdgcn_raw_buffer_load_b16(prs, qvoff, srow + (unsigned)(ii * GINP * 2), 0);
;                                                        kv[ii] = __builtin_amdgcn_raw_buffer_load_b16(prs, qvoff + 1024u, srow + (unsigned)(ii * GINP * 2), 0); }
;                     unsigned vw[16];
; #pragma unroll
;                     for (int ii = 0; ii < 16; ++ii) vw[ii] = __builtin_amdgcn_raw_buffer_load_b32(prs, vvoff, srow + (unsigned)(ii * GINP * 2), 0);
.LBB0_217:
	s_and_b64 vcc, exec, s[6:7]
	s_cbranch_vccz .LBB0_212
	s_nop 7
	v_lshl_or_b32 v0, s8, 13, v198
	s_lshl_b32 s0, s15, 7
	v_or_b32_e32 v0, s0, v0
	v_lshlrev_b32_e32 v160, 2, v0
	v_lshl_add_u64 v[0:1], s[16:17], 0, v[160:161]
	v_lshl_add_u64 v[0:1], s[22:23], 2, v[0:1]
	v_mov_b32_e32 v193, v161
	v_lshl_add_u64 v[0:1], v[0:1], 0, v[192:193]
	global_load_dword v2, v[0:1], off
	global_load_dword v3, v[0:1], off offset:2048
	s_movk_i32 s6, 0x1000
	s_lshl_b32 s9, s9, 11
	v_lshlrev_b32_e32 v160, 2, v188
	s_mov_b32 s20, 0
	v_or_b32_e32 v52, s9, v186
	s_waitcnt vmcnt(0)
	v_cvt_pk_bf16_f32 v32, v2, v3
	v_lshlrev_b32_e32 v4, 16, v32
	v_and_b32_e32 v5, 0xffff0000, v32
	v_pk_add_f32 v[2:3], v[2:3], v[4:5] neg_lo:[0,1] neg_hi:[0,1]
	s_nop 0
	v_cvt_pk_bf16_f32 v36, v2, v3
	v_add_co_u32_e32 v2, vcc, s6, v0
	s_movk_i32 s6, 0x2000
	s_nop 0
	v_addc_co_u32_e32 v3, vcc, 0, v1, vcc
	v_add_co_u32_e32 v4, vcc, s6, v0
	s_movk_i32 s6, 0x3000
	s_nop 0
	v_addc_co_u32_e32 v5, vcc, 0, v1, vcc
	global_load_dword v6, v[4:5], off offset:-4096
	global_load_dword v7, v[2:3], off offset:2048
	v_add_co_u32_e32 v0, vcc, s6, v0
	s_lshl_b32 s6, s8, 9
	s_nop 0
	v_addc_co_u32_e32 v1, vcc, 0, v1, vcc
	s_or_b32 s6, s0, s6
	s_cmp_lg_u32 s8, 0
	s_cselect_b64 s[68:69], -1, 0
	s_cmp_eq_u32 s8, 0
	s_cselect_b64 s[48:49], -1, 0
	s_waitcnt vmcnt(0)
	v_cvt_pk_bf16_f32 v33, v6, v7
	v_lshlrev_b32_e32 v2, 16, v33
	v_and_b32_e32 v3, 0xffff0000, v33
	v_pk_add_f32 v[2:3], v[6:7], v[2:3] neg_lo:[0,1] neg_hi:[0,1]
	s_nop 0
	v_cvt_pk_bf16_f32 v37, v2, v3
	global_load_dword v2, v[4:5], off
	global_load_dword v3, v[4:5], off offset:2048
	s_waitcnt vmcnt(0)
	v_cvt_pk_bf16_f32 v34, v2, v3
	v_lshlrev_b32_e32 v4, 16, v34
	v_and_b32_e32 v5, 0xffff0000, v34
	v_pk_add_f32 v[2:3], v[2:3], v[4:5] neg_lo:[0,1] neg_hi:[0,1]
	s_nop 0
	v_cvt_pk_bf16_f32 v38, v2, v3
	global_load_dword v2, v[0:1], off
	global_load_dword v3, v[0:1], off offset:2048
	s_waitcnt vmcnt(0)
	v_cvt_pk_bf16_f32 v35, v2, v3
	v_lshlrev_b32_e32 v0, 16, v35
	v_and_b32_e32 v1, 0xffff0000, v35
	v_pk_add_f32 v[0:1], v[2:3], v[0:1] neg_lo:[0,1] neg_hi:[0,1]
	s_nop 0
	v_cvt_pk_bf16_f32 v39, v0, v1
	v_add_u32_e32 v0, s6, v199
	v_ashrrev_i32_e32 v1, 31, v0
	v_lshl_add_u64 v[0:1], v[0:1], 2, s[18:19]
	global_load_dword v0, v[0:1], off
	v_or_b32_e32 v1, s0, v200
	s_and_b64 s[6:7], s[48:49], exec
	v_lshlrev_b32_e32 v50, 1, v1
	v_lshl_or_b32 v1, s15, 9, v213
	s_cselect_b32 s0, 0, 0x7e0
	v_or_b32_e32 v51, 0x800, v1
	v_or_b32_e32 v1, s0, v186
	v_or_b32_e32 v2, s9, v1
	v_ashrrev_i32_e32 v3, 31, v2
	v_readlane_b32 s6, v253, 19
	v_lshlrev_b64 v[2:3], 7, v[2:3]
	v_readlane_b32 s7, v253, 20
	s_lshl_b32 s28, s8, 6
	v_lshl_add_u64 v[48:49], v[190:191], 0, s[28:29]
	v_lshl_add_u64 v[2:3], s[6:7], 0, v[2:3]
	v_lshl_add_u64 v[2:3], v[2:3], 0, s[28:29]
	v_lshl_add_u64 v[2:3], v[2:3], 0, v[160:161]
	global_load_dwordx4 v[40:43], v[2:3], off offset:16
	global_load_dwordx4 v[44:47], v[2:3], off
	v_or_b32_e32 v53, 0x400, v50
	s_xor_b64 s[50:51], s[40:41], s[48:49]
	s_xor_b64 s[52:53], s[42:43], s[48:49]
	s_xor_b64 s[54:55], s[44:45], s[48:49]
	s_xor_b64 s[56:57], s[46:47], s[48:49]
	s_mov_b32 s8, 63
	s_waitcnt vmcnt(2)
	v_mov_b32_e32 v1, v0
	v_mov_b32_e32 v2, v0
	v_mov_b32_e32 v3, v0
	v_mov_b32_e32 v4, v0
	v_mov_b32_e32 v5, v0
	v_mov_b32_e32 v6, v0
	v_mov_b32_e32 v7, v0
	v_mov_b32_e32 v8, v0
	v_mov_b32_e32 v9, v0
	v_mov_b32_e32 v10, v0
	v_mov_b32_e32 v11, v0
	v_mov_b32_e32 v12, v0
	v_mov_b32_e32 v13, v0
	v_mov_b32_e32 v14, v0
	v_mov_b32_e32 v15, v0
	v_and_b32_e32 v171, 7, v179
	v_lshrrev_b32_e32 v175, 3, v179
	v_mul_u32_u24_e32 v176, 0x6800, v171
	v_lshl_add_u32 v176, v175, 4, v176
	s_lshl_b32 s0, s15, 9
	s_addk_i32 s0, 0x800
	v_add_u32_e32 v176, s0, v176
	v_mul_u32_u24_e32 v177, 0x280, v175
	v_lshl_add_u32 v177, v171, 3, v177
	v_and_b32_e32 v172, 15, v179
	v_lshlrev_b32_e32 v172, 4, v172
	v_bfe_u32 v174, v179, 4, 2
	v_lshrrev_b32_e32 v173, 6, v179
	v_lshl_add_u32 v174, v173, 3, v174
	v_mul_u32_u24_e32 v174, 0x1a00, v174
	v_add_u32_e32 v172, v172, v174
	s_lshl_b32 s0, s15, 8
	v_add_u32_e32 v172, s0, v172
	v_lshlrev_b32_e32 v174, 11, v173
	v_add_u32_e32 v174, 0x1b600, v174
	v_and_b32_e32 v173, 0x7f, v179
	v_lshlrev_b32_e32 v173, 1, v173
	v_bfe_u32 v175, v179, 7, 1
	v_lshl_add_u32 v173, v175, 12, v173
	v_add_u32_e32 v173, 0x1b600, v173
	s_and_b64 s[6:7], s[48:49], exec
	s_cselect_b32 s0, s20, s8
	s_lshl_b32 s0, s0, 5
	s_add_i32 s0, s0, s9
	s_mulk_i32 s0, 0x1a00
	v_readfirstlane_b32 s26, v174
	s_add_u32 s78, s64, s0
	s_addc_u32 s79, s65, 0
	s_add_u32 s80, s78, 0x6800
	s_addc_u32 s81, s79, 0
	s_add_u32 s82, s78, 0x400
	s_addc_u32 s83, s79, 0
	s_add_u32 s24, s80, 0x400
	s_addc_u32 s25, s81, 0
	s_mov_b32 m0, s26
	s_nop 0
	global_load_lds_dwordx4 v172, s[78:79]
	s_add_i32 m0, s26, 0x400
	s_nop 0
	global_load_lds_dwordx4 v172, s[80:81]
	s_add_i32 m0, s26, 0x2000
	s_nop 0
	global_load_lds_dwordx4 v172, s[82:83]
	s_add_i32 m0, s26, 0x2400
	s_nop 0
	global_load_lds_dwordx4 v172, s[24:25]
	s_setprio 1
	s_branch .LBB0_220
